# stack: prep-phase rebalance + conv remap + wide V^T stores + barrier tweaks (early L2 write-back by first arriver, early L1 invalidate, poll top counter)
# speedup vs baseline: 1.0059x; 1.0059x over previous
.LBB0_1934:
	s_or_b64 exec, exec, s[2:3]
	v_cvt_f32_u32_e32 v5, v3
	s_waitcnt vmcnt(0)
	buffer_inv sc1
	v_readfirstlane_b32 s2, v4
	v_sub_u32_e32 v4, 0, v3
	v_rcp_iflag_f32_e32 v5, v5
	v_add_u32_e32 v6, s2, v0
	v_mul_f32_e32 v5, 0x4f7ffffe, v5
	v_cvt_u32_f32_e32 v5, v5
	v_mul_lo_u32 v0, v4, v5
	v_mul_hi_u32 v0, v5, v0
	v_add_u32_e32 v0, v5, v0
	v_mul_hi_u32 v0, v6, v0
	v_mul_lo_u32 v4, v0, v3
	v_sub_u32_e32 v4, v6, v4
	v_add_u32_e32 v5, 1, v0
	v_cmp_ge_u32_e32 vcc, v4, v3
	s_nop 1
	v_cndmask_b32_e32 v0, v0, v5, vcc
	v_sub_u32_e32 v5, v4, v3
	v_cndmask_b32_e32 v4, v4, v5, vcc
	v_add_u32_e32 v5, 1, v0
	v_cmp_ge_u32_e32 vcc, v4, v3
	v_add_u32_e32 v4, 1, v6
	s_nop 0
	v_cndmask_b32_e32 v0, v0, v5, vcc
	v_mul_lo_u32 v5, v3, v0
	v_cmp_eq_u32_e32 vcc, v6, v5
	s_cbranch_vccz .Lef_skip
	buffer_wbl2 sc1
.Lef_skip:
	v_add_u32_e32 v3, v5, v3
	v_cmp_ne_u32_e32 vcc, v4, v3
	s_and_saveexec_b64 s[2:3], vcc
	s_xor_b64 s[2:3], exec, s[2:3]
	s_cbranch_execz .LBB0_1948
	v_readlane_b32 s4, v254, 29
	v_readlane_b32 s5, v254, 30
	s_waitcnt lgkmcnt(0)
	v_add_u32_e32 v7, 1, v0
	v_mul_lo_u32 v7, v7, v2
	s_nop 3
	global_load_dword v2, v1, s[4:5] offset:-256 sc1
	s_waitcnt vmcnt(0)
	v_cmp_lt_u32_e32 vcc, v2, v7
	s_and_saveexec_b64 s[4:5], vcc
	s_cbranch_execz .LBB0_1947
	s_mov_b32 s17, 1
	s_mov_b64 s[6:7], 0
	s_branch .LBB0_1938
